# attention: waves 4-7 start each unit ~640 cycles late (stagger SIMD partners)
# speedup vs baseline: 1.0102x; 1.0102x over previous
.LBB0_830:
	s_cmp_eq_u32 s29, 0
	s_cbranch_scc1 .Lattn_nostag
	s_sleep 10
